# C1 LoRA loop: k-pair weights requested three iterations ahead (3 landing register sets, unrolled by 3) instead of one ahead with vmcnt(0) each iteration
# speedup vs baseline: 1.0166x; 1.0008x over previous
; __global__ void __launch_bounds__(NWAVES * 64, 2) mk_fwd(Args args) {
;     ...
;                     unsigned pur[17], puk[17], puv[17];
; #pragma unroll
;                     for (int tok = 0; tok < 17; ++tok) { if (tok == 0 && first) { pur[0] = puk[0] = puv[0] = 0u; continue; }
;                         const bf16_t* pp = proj + (size_t)(m0 + tok - 1) * NPAD + c0; pur[tok] = *(const unsigned*)pp; puk[tok] = *(const unsigned*)(pp + RW); puv[tok] = *(const unsigned*)(pp + 2 * RW); }
;                     float lw[16][2], la[16][2];
; #pragma unroll
;                     for (int t = 0; t < 16; ++t) { lw[t][0] = 0.f; lw[t][1] = 0.f; la[t][0] = 0.f; la[t][1] = 0.f; }
;                     u32x2 wvn = *(const u32x2*)(w2pl + c0), avn = *(const u32x2*)(w2pl + (size_t)32 * RW + c0);
;                     for (int ip = 0; ip < 32; ++ip) {
;                         const u32x2 wv = wvn, av = avn;
;                         { const int ipn = ip < 31 ? ip + 1 : 31; wvn = *(const u32x2*)(w2pl + (size_t)ipn * RW + c0); avn = *(const u32x2*)(w2pl + (size_t)(32 + ipn) * RW + c0); }
.LBB0_459:
	v_mad_i64_i32 v[4:5], s[56:57], s80, v198, v[60:61]
	v_add_co_u32_e32 v6, vcc, 0x1000, v4
	s_or_b32 s90, s80, 1
	s_nop 0
	v_addc_co_u32_e32 v7, vcc, 0, v5, vcc
	v_mad_i64_i32 v[8:9], s[56:57], s90, v198, v[60:61]
	v_add_co_u32_e32 v10, vcc, 0x1000, v8
	s_or_b32 s86, s80, 2
	s_nop 0
	v_addc_co_u32_e32 v11, vcc, 0, v9, vcc
	v_mad_i64_i32 v[12:13], s[56:57], s86, v198, v[60:61]
	v_add_co_u32_e32 v14, vcc, 0x1000, v12
	s_or_b32 s82, s80, 3
	s_nop 0
	v_addc_co_u32_e32 v15, vcc, 0, v13, vcc
	v_mad_i64_i32 v[16:17], s[56:57], s82, v198, v[60:61]
	global_load_dword v224, v[6:7], off
	global_load_dword v221, v[8:9], off
	global_load_dword v220, v[8:9], off offset:2048
	global_load_dword v216, v[10:11], off
	global_load_dword v214, v[12:13], off
	global_load_dword v213, v[12:13], off offset:2048
	global_load_dword v210, v[14:15], off
	global_load_dword v206, v[16:17], off
	v_add_co_u32_e32 v6, vcc, 0x1000, v16
	s_or_b32 s78, s80, 4
	s_nop 0
	v_addc_co_u32_e32 v7, vcc, 0, v17, vcc
	v_mad_i64_i32 v[8:9], s[56:57], s78, v198, v[60:61]
	v_add_co_u32_e32 v10, vcc, 0x1000, v8
	s_or_b32 s76, s80, 5
	s_nop 0
	v_addc_co_u32_e32 v11, vcc, 0, v9, vcc
	v_mad_i64_i32 v[12:13], s[56:57], s76, v198, v[60:61]
	v_add_co_u32_e32 v14, vcc, 0x1000, v12
	s_or_b32 s74, s80, 6
	s_nop 0
	v_addc_co_u32_e32 v15, vcc, 0, v13, vcc
	global_load_dword v207, v[16:17], off offset:2048
	global_load_dword v187, v[6:7], off
	global_load_dword v182, v[8:9], off
	global_load_dword v181, v[8:9], off offset:2048
	global_load_dword v180, v[10:11], off
	global_load_dword v175, v[12:13], off
	global_load_dword v174, v[12:13], off offset:2048
	global_load_dword v173, v[14:15], off
	v_mad_i64_i32 v[6:7], s[56:57], s74, v198, v[60:61]
	v_add_co_u32_e32 v8, vcc, 0x1000, v6
	s_or_b32 s72, s80, 7
	s_nop 0
	v_addc_co_u32_e32 v9, vcc, 0, v7, vcc
	v_mad_i64_i32 v[10:11], s[56:57], s72, v198, v[60:61]
	v_add_co_u32_e32 v12, vcc, 0x1000, v10
	s_or_b32 s70, s80, 8
	s_nop 0
	v_addc_co_u32_e32 v13, vcc, 0, v11, vcc
	v_mad_i64_i32 v[14:15], s[56:57], s70, v198, v[60:61]
	global_load_dword v162, v[6:7], off
	global_load_dword v161, v[6:7], off offset:2048
	global_load_dword v158, v[8:9], off
	global_load_dword v156, v[10:11], off
	global_load_dword v155, v[10:11], off offset:2048
	global_load_dword v151, v[12:13], off
	global_load_dword v148, v[14:15], off
	global_load_dword v147, v[14:15], off offset:2048
	v_add_co_u32_e32 v6, vcc, 0x1000, v14
	s_or_b32 s68, s80, 9
	s_nop 0
	v_addc_co_u32_e32 v7, vcc, 0, v15, vcc
	v_mad_i64_i32 v[8:9], s[56:57], s68, v198, v[60:61]
	v_add_co_u32_e32 v10, vcc, 0x1000, v8
	s_or_b32 s66, s80, 10
	s_nop 0
	v_addc_co_u32_e32 v11, vcc, 0, v9, vcc
	v_mad_i64_i32 v[12:13], s[56:57], s66, v198, v[60:61]
	v_add_co_u32_e32 v14, vcc, 0x1000, v12
	s_or_b32 s64, s80, 11
	s_nop 0
	v_addc_co_u32_e32 v15, vcc, 0, v13, vcc
	v_mad_i64_i32 v[16:17], s[56:57], s64, v198, v[60:61]
	global_load_dword v144, v[6:7], off
	global_load_dword v143, v[8:9], off
	global_load_dword v142, v[8:9], off offset:2048
	global_load_dword v138, v[10:11], off
	global_load_dword v137, v[12:13], off
	global_load_dword v136, v[12:13], off offset:2048
	global_load_dword v131, v[14:15], off
	global_load_dword v129, v[16:17], off
	v_add_co_u32_e32 v6, vcc, 0x1000, v16
	s_or_b32 s62, s80, 12
	s_nop 0
	v_addc_co_u32_e32 v7, vcc, 0, v17, vcc
	v_mad_i64_i32 v[8:9], s[56:57], s62, v198, v[60:61]
	v_add_co_u32_e32 v10, vcc, 0x1000, v8
	s_or_b32 s60, s80, 13
	s_nop 0
	v_addc_co_u32_e32 v11, vcc, 0, v9, vcc
	v_mad_i64_i32 v[12:13], s[56:57], s60, v198, v[60:61]
	v_add_co_u32_e32 v14, vcc, 0x1000, v12
	s_or_b32 s58, s80, 14
	s_nop 0
	v_addc_co_u32_e32 v15, vcc, 0, v13, vcc
	global_load_dword v130, v[16:17], off offset:2048
	global_load_dword v125, v[6:7], off
	global_load_dword v121, v[8:9], off
	global_load_dword v120, v[8:9], off offset:2048
	global_load_dword v117, v[10:11], off
	global_load_dword v114, v[12:13], off
	global_load_dword v113, v[12:13], off offset:2048
	global_load_dword v110, v[14:15], off
	v_mad_i64_i32 v[6:7], s[56:57], s58, v198, v[60:61]
	v_add_co_u32_e32 v8, vcc, 0x1000, v6
	s_or_b32 s56, s80, 15
	s_nop 0
	v_addc_co_u32_e32 v9, vcc, 0, v7, vcc
	v_mad_i64_i32 v[10:11], vcc, s56, v198, v[60:61]
	v_add_co_u32_e32 v12, vcc, 0x1000, v10
	s_ashr_i32 s81, s80, 31
	s_nop 0
	v_addc_co_u32_e32 v13, vcc, 0, v11, vcc
	global_load_dword v106, v[6:7], off
	global_load_dword v105, v[6:7], off offset:2048
	global_load_dword v104, v[8:9], off
	global_load_dword v99, v[10:11], off
	global_load_dword v98, v[10:11], off offset:2048
	global_load_dword v97, v[12:13], off
	global_load_dword v235, v[4:5], off
	global_load_dword v234, v[4:5], off offset:2048
	global_load_dwordx2 v[244:245], v[62:63], off
	global_load_dwordx2 v[246:247], v[64:65], off
	s_mov_b64 s[94:95], 0x1000
	v_add_co_u32_e32 v248, vcc, s44, v72
	s_nop 1
	v_addc_co_u32_e32 v249, vcc, 0, v73, vcc
	global_load_dwordx2 v[74:75], v[72:73], off
	global_load_dwordx2 v[76:77], v[248:249], off
	v_lshl_add_u64 v[4:5], v[72:73], 0, s[94:95]
	v_lshl_add_u64 v[248:249], v[248:249], 0, s[94:95]
	global_load_dwordx2 v[240:241], v[4:5], off
	global_load_dwordx2 v[242:243], v[248:249], off
	v_lshl_add_u64 v[4:5], v[4:5], 0, s[94:95]
	v_lshl_add_u64 v[248:249], v[248:249], 0, s[94:95]
	s_mov_b32 s92, 0
	s_ashr_i32 s91, s90, 31
	s_ashr_i32 s87, s86, 31
	s_ashr_i32 s83, s82, 31
	s_ashr_i32 s79, s78, 31
	s_ashr_i32 s77, s76, 31
	s_ashr_i32 s75, s74, 31
	s_ashr_i32 s73, s72, 31
	s_ashr_i32 s71, s70, 31
	s_ashr_i32 s69, s68, 31
	s_ashr_i32 s67, s66, 31
	s_ashr_i32 s65, s64, 31
	s_ashr_i32 s63, s62, 31
	s_ashr_i32 s61, s60, 31
	s_ashr_i32 s59, s58, 31
	s_ashr_i32 s57, s56, 31
; #define LAS __attribute__((address_space(3)))
; #define DOT2(a_, b_, c_) __builtin_amdgcn_fdot2_f32_bf16(__builtin_bit_cast(bf16x2_t, (unsigned)(a_)), __builtin_bit_cast(bf16x2_t, (unsigned)(b_)), (c_), false)
; __global__ void __launch_bounds__(NWAVES * 64, 2) mk_fwd(Args args) {
;     ...
;                     float lw[16][2], la[16][2];
; #pragma unroll
;                     for (int t = 0; t < 16; ++t) { lw[t][0] = 0.f; lw[t][1] = 0.f; la[t][0] = 0.f; la[t][1] = 0.f; }
;                     u32x2 wvn = *(const u32x2*)(w2pl + c0), avn = *(const u32x2*)(w2pl + (size_t)32 * RW + c0);
;                     for (int ip = 0; ip < 32; ++ip) {
;                         const u32x2 wv = wvn, av = avn;
;                         { const int ipn = ip < 31 ? ip + 1 : 31; wvn = *(const u32x2*)(w2pl + (size_t)ipn * RW + c0); avn = *(const u32x2*)(w2pl + (size_t)(32 + ipn) * RW + c0); }
; #pragma unroll
;                         for (int tq = 0; tq < 4; ++tq) { const u32x4 x4 = *(LAS const u32x4*)(actP + ip * 16 + tq * 4), y4 = *(LAS const u32x4*)(actP + (32 + ip) * 16 + tq * 4);
; #pragma unroll
;                             for (int e = 0; e < 4; ++e) { lw[tq * 4 + e][0] = DOT2(x4[e], wv.x, lw[tq * 4 + e][0]); lw[tq * 4 + e][1] = DOT2(x4[e], wv.y, lw[tq * 4 + e][1]);
;                                                           la[tq * 4 + e][0] = DOT2(y4[e], av.x, la[tq * 4 + e][0]); la[tq * 4 + e][1] = DOT2(y4[e], av.y, la[tq * 4 + e][1]); } }
	v_mov_b32_e32 v149, 0
	v_mov_b32_e32 v150, 0
	v_mov_b32_e32 v154, 0
	v_mov_b32_e32 v157, 0
	v_mov_b32_e32 v163, 0
	v_mov_b32_e32 v172, 0
	v_mov_b32_e32 v178, 0
	v_mov_b32_e32 v179, 0
	v_mov_b32_e32 v185, 0
	v_mov_b32_e32 v186, 0
	v_mov_b32_e32 v211, 0
	v_mov_b32_e32 v212, 0
	v_mov_b32_e32 v218, 0
	v_mov_b32_e32 v219, 0
	v_mov_b32_e32 v225, 0
	v_mov_b32_e32 v226, 0
	v_mov_b32_e32 v230, 0
	v_mov_b32_e32 v231, 0
	v_mov_b32_e32 v236, 0
	v_mov_b32_e32 v237, 0
	v_mov_b32_e32 v141, 0
	v_mov_b32_e32 v135, 0
	v_mov_b32_e32 v134, 0
	v_mov_b32_e32 v128, 0
	v_mov_b32_e32 v126, 0
	v_mov_b32_e32 v119, 0
	v_mov_b32_e32 v118, 0
	v_mov_b32_e32 v112, 0
	v_mov_b32_e32 v111, 0
	v_mov_b32_e32 v103, 0
	v_mov_b32_e32 v102, 0
	v_mov_b32_e32 v233, 0
	v_mov_b32_e32 v232, 0
	v_mov_b32_e32 v229, 0
	v_mov_b32_e32 v228, 0
	v_mov_b32_e32 v223, 0
	v_mov_b32_e32 v222, 0
	v_mov_b32_e32 v217, 0
	v_mov_b32_e32 v215, 0
	v_mov_b32_e32 v209, 0
	v_mov_b32_e32 v208, 0
	v_mov_b32_e32 v184, 0
	v_mov_b32_e32 v183, 0
	v_mov_b32_e32 v177, 0
	v_mov_b32_e32 v176, 0
	v_mov_b32_e32 v160, 0
	v_mov_b32_e32 v159, 0
	v_mov_b32_e32 v153, 0
	v_mov_b32_e32 v152, 0
	v_mov_b32_e32 v146, 0
	v_mov_b32_e32 v145, 0
	v_mov_b32_e32 v140, 0
	v_mov_b32_e32 v139, 0
	v_mov_b32_e32 v133, 0
	v_mov_b32_e32 v132, 0
	v_mov_b32_e32 v124, 0
	v_mov_b32_e32 v123, 0
	v_mov_b32_e32 v116, 0
	v_mov_b32_e32 v115, 0
	v_mov_b32_e32 v108, 0
	v_mov_b32_e32 v107, 0
	v_mov_b32_e32 v101, 0
	v_mov_b32_e32 v100, 0
	s_mov_b64 s[94:95], 0x1000
.LBB0_460:
	s_waitcnt vmcnt(4)
	v_mov_b64_e32 v[28:29], v[244:245]
	v_mov_b64_e32 v[6:7], v[246:247]
	global_load_dwordx2 v[244:245], v[4:5], off
	global_load_dwordx2 v[246:247], v[248:249], off
	s_add_i32 s93, s92, 0
	v_mov_b32_e32 v30, s93
	ds_read_b128 v[8:11], v30 offset:2048
	ds_read_b128 v[12:15], v30
	ds_read_b128 v[16:19], v30 offset:16
	ds_read_b128 v[20:23], v30 offset:32
	ds_read_b128 v[24:27], v30 offset:48
	s_waitcnt lgkmcnt(4)
	v_dot2c_f32_bf16_e32 v237, v8, v6
	v_dot2c_f32_bf16_e32 v236, v8, v7
	v_dot2c_f32_bf16_e32 v231, v9, v6
	v_dot2c_f32_bf16_e32 v230, v9, v7
	v_dot2c_f32_bf16_e32 v226, v10, v6
	v_dot2c_f32_bf16_e32 v225, v10, v7
	v_dot2c_f32_bf16_e32 v219, v11, v6
	v_dot2c_f32_bf16_e32 v218, v11, v7
	ds_read_b128 v[8:11], v30 offset:2064
	s_add_i32 s92, s92, 64
	s_waitcnt lgkmcnt(4)
	v_dot2c_f32_bf16_e32 v233, v12, v28
	v_dot2c_f32_bf16_e32 v232, v12, v29
	v_dot2c_f32_bf16_e32 v229, v13, v28
	s_waitcnt lgkmcnt(0)
	v_dot2c_f32_bf16_e32 v212, v8, v6
	v_dot2c_f32_bf16_e32 v211, v8, v7
	v_dot2c_f32_bf16_e32 v186, v9, v6
	v_dot2c_f32_bf16_e32 v185, v9, v7
	v_dot2c_f32_bf16_e32 v179, v10, v6
	v_dot2c_f32_bf16_e32 v178, v10, v7
	v_dot2c_f32_bf16_e32 v172, v11, v6
	v_dot2c_f32_bf16_e32 v163, v11, v7
	ds_read_b128 v[8:11], v30 offset:2080
	v_dot2c_f32_bf16_e32 v228, v13, v29
	v_dot2c_f32_bf16_e32 v223, v14, v28
	v_dot2c_f32_bf16_e32 v222, v14, v29
	v_dot2c_f32_bf16_e32 v217, v15, v28
	s_waitcnt lgkmcnt(0)
	v_dot2c_f32_bf16_e32 v157, v8, v6
	v_dot2c_f32_bf16_e32 v154, v8, v7
	v_dot2c_f32_bf16_e32 v150, v9, v6
	v_dot2c_f32_bf16_e32 v149, v9, v7
	v_dot2c_f32_bf16_e32 v122, v10, v6
	v_dot2c_f32_bf16_e32 v141, v10, v7
	v_dot2c_f32_bf16_e32 v135, v11, v6
	v_dot2c_f32_bf16_e32 v134, v11, v7
	ds_read_b128 v[8:11], v30 offset:2096
	v_dot2c_f32_bf16_e32 v215, v15, v29
	v_dot2c_f32_bf16_e32 v209, v16, v28
	v_dot2c_f32_bf16_e32 v208, v16, v29
	v_dot2c_f32_bf16_e32 v184, v17, v28
	v_dot2c_f32_bf16_e32 v183, v17, v29
	v_dot2c_f32_bf16_e32 v177, v18, v28
	v_dot2c_f32_bf16_e32 v176, v18, v29
	v_dot2c_f32_bf16_e32 v160, v19, v28
	v_dot2c_f32_bf16_e32 v159, v19, v29
	v_dot2c_f32_bf16_e32 v153, v20, v28
	v_dot2c_f32_bf16_e32 v152, v20, v29
	v_dot2c_f32_bf16_e32 v146, v21, v28
	v_dot2c_f32_bf16_e32 v145, v21, v29
	v_dot2c_f32_bf16_e32 v140, v22, v28
	v_dot2c_f32_bf16_e32 v139, v22, v29
	v_dot2c_f32_bf16_e32 v133, v23, v28
	v_dot2c_f32_bf16_e32 v132, v23, v29
	v_dot2c_f32_bf16_e32 v124, v24, v28
	v_dot2c_f32_bf16_e32 v123, v24, v29
	s_waitcnt lgkmcnt(0)
	v_dot2c_f32_bf16_e32 v128, v8, v6
	v_dot2c_f32_bf16_e32 v126, v8, v7
	v_dot2c_f32_bf16_e32 v116, v25, v28
	v_dot2c_f32_bf16_e32 v115, v25, v29
	v_dot2c_f32_bf16_e32 v119, v9, v6
	v_dot2c_f32_bf16_e32 v118, v9, v7
	v_dot2c_f32_bf16_e32 v108, v26, v28
	v_dot2c_f32_bf16_e32 v107, v26, v29
	v_dot2c_f32_bf16_e32 v112, v10, v6
	v_dot2c_f32_bf16_e32 v111, v10, v7
	v_dot2c_f32_bf16_e32 v101, v27, v28
	v_dot2c_f32_bf16_e32 v100, v27, v29
	v_dot2c_f32_bf16_e32 v103, v11, v6
	v_dot2c_f32_bf16_e32 v102, v11, v7
	v_lshl_add_u64 v[4:5], v[4:5], 0, s[94:95]
	v_lshl_add_u64 v[248:249], v[248:249], 0, s[94:95]
	s_waitcnt vmcnt(4)
	v_mov_b64_e32 v[28:29], v[74:75]
	v_mov_b64_e32 v[6:7], v[76:77]
	global_load_dwordx2 v[74:75], v[4:5], off
	global_load_dwordx2 v[76:77], v[248:249], off
	s_add_i32 s93, s92, 0
	v_mov_b32_e32 v30, s93
	ds_read_b128 v[8:11], v30 offset:2048
	ds_read_b128 v[12:15], v30
	ds_read_b128 v[16:19], v30 offset:16
	ds_read_b128 v[20:23], v30 offset:32
	ds_read_b128 v[24:27], v30 offset:48
	s_waitcnt lgkmcnt(4)
	v_dot2c_f32_bf16_e32 v237, v8, v6
	v_dot2c_f32_bf16_e32 v236, v8, v7
	v_dot2c_f32_bf16_e32 v231, v9, v6
	v_dot2c_f32_bf16_e32 v230, v9, v7
	v_dot2c_f32_bf16_e32 v226, v10, v6
	v_dot2c_f32_bf16_e32 v225, v10, v7
	v_dot2c_f32_bf16_e32 v219, v11, v6
	v_dot2c_f32_bf16_e32 v218, v11, v7
	ds_read_b128 v[8:11], v30 offset:2064
	s_add_i32 s92, s92, 64
	s_waitcnt lgkmcnt(4)
	v_dot2c_f32_bf16_e32 v233, v12, v28
	v_dot2c_f32_bf16_e32 v232, v12, v29
	v_dot2c_f32_bf16_e32 v229, v13, v28
	s_waitcnt lgkmcnt(0)
; #define LAS __attribute__((address_space(3)))
; #define DOT2(a_, b_, c_) __builtin_amdgcn_fdot2_f32_bf16(__builtin_bit_cast(bf16x2_t, (unsigned)(a_)), __builtin_bit_cast(bf16x2_t, (unsigned)(b_)), (c_), false)
; __global__ void __launch_bounds__(NWAVES * 64, 2) mk_fwd(Args args) {
;     ...
;                     for (int ip = 0; ip < 32; ++ip) {
;                         const u32x2 wv = wvn, av = avn;
;                         { const int ipn = ip < 31 ? ip + 1 : 31; wvn = *(const u32x2*)(w2pl + (size_t)ipn * RW + c0); avn = *(const u32x2*)(w2pl + (size_t)(32 + ipn) * RW + c0); }
; #pragma unroll
;                         for (int tq = 0; tq < 4; ++tq) { const u32x4 x4 = *(LAS const u32x4*)(actP + ip * 16 + tq * 4), y4 = *(LAS const u32x4*)(actP + (32 + ip) * 16 + tq * 4);
; #pragma unroll
;                             for (int e = 0; e < 4; ++e) { lw[tq * 4 + e][0] = DOT2(x4[e], wv.x, lw[tq * 4 + e][0]); lw[tq * 4 + e][1] = DOT2(x4[e], wv.y, lw[tq * 4 + e][1]);
;                                                           la[tq * 4 + e][0] = DOT2(y4[e], av.x, la[tq * 4 + e][0]); la[tq * 4 + e][1] = DOT2(y4[e], av.y, la[tq * 4 + e][1]); } }
	v_dot2c_f32_bf16_e32 v212, v8, v6
	v_dot2c_f32_bf16_e32 v211, v8, v7
	v_dot2c_f32_bf16_e32 v186, v9, v6
	v_dot2c_f32_bf16_e32 v185, v9, v7
	v_dot2c_f32_bf16_e32 v179, v10, v6
	v_dot2c_f32_bf16_e32 v178, v10, v7
	v_dot2c_f32_bf16_e32 v172, v11, v6
	v_dot2c_f32_bf16_e32 v163, v11, v7
	ds_read_b128 v[8:11], v30 offset:2080
	v_dot2c_f32_bf16_e32 v228, v13, v29
	v_dot2c_f32_bf16_e32 v223, v14, v28
	v_dot2c_f32_bf16_e32 v222, v14, v29
	v_dot2c_f32_bf16_e32 v217, v15, v28
	s_waitcnt lgkmcnt(0)
	v_dot2c_f32_bf16_e32 v157, v8, v6
	v_dot2c_f32_bf16_e32 v154, v8, v7
	v_dot2c_f32_bf16_e32 v150, v9, v6
	v_dot2c_f32_bf16_e32 v149, v9, v7
	v_dot2c_f32_bf16_e32 v122, v10, v6
	v_dot2c_f32_bf16_e32 v141, v10, v7
	v_dot2c_f32_bf16_e32 v135, v11, v6
	v_dot2c_f32_bf16_e32 v134, v11, v7
	ds_read_b128 v[8:11], v30 offset:2096
	v_dot2c_f32_bf16_e32 v215, v15, v29
	v_dot2c_f32_bf16_e32 v209, v16, v28
	v_dot2c_f32_bf16_e32 v208, v16, v29
	v_dot2c_f32_bf16_e32 v184, v17, v28
	v_dot2c_f32_bf16_e32 v183, v17, v29
	v_dot2c_f32_bf16_e32 v177, v18, v28
	v_dot2c_f32_bf16_e32 v176, v18, v29
	v_dot2c_f32_bf16_e32 v160, v19, v28
	v_dot2c_f32_bf16_e32 v159, v19, v29
	v_dot2c_f32_bf16_e32 v153, v20, v28
	v_dot2c_f32_bf16_e32 v152, v20, v29
	v_dot2c_f32_bf16_e32 v146, v21, v28
	v_dot2c_f32_bf16_e32 v145, v21, v29
	v_dot2c_f32_bf16_e32 v140, v22, v28
	v_dot2c_f32_bf16_e32 v139, v22, v29
	v_dot2c_f32_bf16_e32 v133, v23, v28
	v_dot2c_f32_bf16_e32 v132, v23, v29
	v_dot2c_f32_bf16_e32 v124, v24, v28
	v_dot2c_f32_bf16_e32 v123, v24, v29
	s_waitcnt lgkmcnt(0)
	v_dot2c_f32_bf16_e32 v128, v8, v6
	v_dot2c_f32_bf16_e32 v126, v8, v7
	v_dot2c_f32_bf16_e32 v116, v25, v28
	v_dot2c_f32_bf16_e32 v115, v25, v29
	v_dot2c_f32_bf16_e32 v119, v9, v6
	v_dot2c_f32_bf16_e32 v118, v9, v7
	v_dot2c_f32_bf16_e32 v108, v26, v28
	v_dot2c_f32_bf16_e32 v107, v26, v29
	v_dot2c_f32_bf16_e32 v112, v10, v6
	v_dot2c_f32_bf16_e32 v111, v10, v7
	v_dot2c_f32_bf16_e32 v101, v27, v28
	v_dot2c_f32_bf16_e32 v100, v27, v29
	v_dot2c_f32_bf16_e32 v103, v11, v6
	v_dot2c_f32_bf16_e32 v102, v11, v7
	v_lshl_add_u64 v[4:5], v[4:5], 0, s[94:95]
	v_lshl_add_u64 v[248:249], v[248:249], 0, s[94:95]
	s_waitcnt vmcnt(4)
	v_mov_b64_e32 v[28:29], v[240:241]
	v_mov_b64_e32 v[6:7], v[242:243]
	global_load_dwordx2 v[240:241], v[4:5], off
	global_load_dwordx2 v[242:243], v[248:249], off
	s_add_i32 s93, s92, 0
	v_mov_b32_e32 v30, s93
	ds_read_b128 v[8:11], v30 offset:2048
	ds_read_b128 v[12:15], v30
	ds_read_b128 v[16:19], v30 offset:16
	ds_read_b128 v[20:23], v30 offset:32
	ds_read_b128 v[24:27], v30 offset:48
	s_waitcnt lgkmcnt(4)
	v_dot2c_f32_bf16_e32 v237, v8, v6
	v_dot2c_f32_bf16_e32 v236, v8, v7
	v_dot2c_f32_bf16_e32 v231, v9, v6
	v_dot2c_f32_bf16_e32 v230, v9, v7
	v_dot2c_f32_bf16_e32 v226, v10, v6
	v_dot2c_f32_bf16_e32 v225, v10, v7
	v_dot2c_f32_bf16_e32 v219, v11, v6
	v_dot2c_f32_bf16_e32 v218, v11, v7
	ds_read_b128 v[8:11], v30 offset:2064
	s_add_i32 s92, s92, 64
	s_waitcnt lgkmcnt(4)
	v_dot2c_f32_bf16_e32 v233, v12, v28
	v_dot2c_f32_bf16_e32 v232, v12, v29
	v_dot2c_f32_bf16_e32 v229, v13, v28
	s_waitcnt lgkmcnt(0)
	v_dot2c_f32_bf16_e32 v212, v8, v6
	v_dot2c_f32_bf16_e32 v211, v8, v7
	v_dot2c_f32_bf16_e32 v186, v9, v6
	v_dot2c_f32_bf16_e32 v185, v9, v7
	v_dot2c_f32_bf16_e32 v179, v10, v6
	v_dot2c_f32_bf16_e32 v178, v10, v7
	v_dot2c_f32_bf16_e32 v172, v11, v6
	v_dot2c_f32_bf16_e32 v163, v11, v7
	ds_read_b128 v[8:11], v30 offset:2080
	v_dot2c_f32_bf16_e32 v228, v13, v29
	v_dot2c_f32_bf16_e32 v223, v14, v28
	v_dot2c_f32_bf16_e32 v222, v14, v29
	v_dot2c_f32_bf16_e32 v217, v15, v28
	s_waitcnt lgkmcnt(0)
	v_dot2c_f32_bf16_e32 v157, v8, v6
	v_dot2c_f32_bf16_e32 v154, v8, v7
	v_dot2c_f32_bf16_e32 v150, v9, v6
	v_dot2c_f32_bf16_e32 v149, v9, v7
	v_dot2c_f32_bf16_e32 v122, v10, v6
	v_dot2c_f32_bf16_e32 v141, v10, v7
	v_dot2c_f32_bf16_e32 v135, v11, v6
	v_dot2c_f32_bf16_e32 v134, v11, v7
	ds_read_b128 v[8:11], v30 offset:2096
	v_dot2c_f32_bf16_e32 v215, v15, v29
	v_dot2c_f32_bf16_e32 v209, v16, v28
	v_dot2c_f32_bf16_e32 v208, v16, v29
	v_dot2c_f32_bf16_e32 v184, v17, v28
	v_dot2c_f32_bf16_e32 v183, v17, v29
	v_dot2c_f32_bf16_e32 v177, v18, v28
	v_dot2c_f32_bf16_e32 v176, v18, v29
	v_dot2c_f32_bf16_e32 v160, v19, v28
	v_dot2c_f32_bf16_e32 v159, v19, v29
	v_dot2c_f32_bf16_e32 v153, v20, v28
	v_dot2c_f32_bf16_e32 v152, v20, v29
	v_dot2c_f32_bf16_e32 v146, v21, v28
	v_dot2c_f32_bf16_e32 v145, v21, v29
	v_dot2c_f32_bf16_e32 v140, v22, v28
	v_dot2c_f32_bf16_e32 v139, v22, v29
	v_dot2c_f32_bf16_e32 v133, v23, v28
	v_dot2c_f32_bf16_e32 v132, v23, v29
	v_dot2c_f32_bf16_e32 v124, v24, v28
	v_dot2c_f32_bf16_e32 v123, v24, v29
	s_waitcnt lgkmcnt(0)
	v_dot2c_f32_bf16_e32 v128, v8, v6
	v_dot2c_f32_bf16_e32 v126, v8, v7
	v_dot2c_f32_bf16_e32 v116, v25, v28
	v_dot2c_f32_bf16_e32 v115, v25, v29
	v_dot2c_f32_bf16_e32 v119, v9, v6
	v_dot2c_f32_bf16_e32 v118, v9, v7
	v_dot2c_f32_bf16_e32 v108, v26, v28
	v_dot2c_f32_bf16_e32 v107, v26, v29
	v_dot2c_f32_bf16_e32 v112, v10, v6
	v_dot2c_f32_bf16_e32 v111, v10, v7
	v_dot2c_f32_bf16_e32 v101, v27, v28
	v_dot2c_f32_bf16_e32 v100, v27, v29
	v_dot2c_f32_bf16_e32 v103, v11, v6
	v_dot2c_f32_bf16_e32 v102, v11, v7
	v_lshl_add_u64 v[4:5], v[4:5], 0, s[94:95]
	v_lshl_add_u64 v[248:249], v[248:249], 0, s[94:95]
	s_cmpk_eq_i32 s92, 0x6c0
	s_cbranch_scc0 .LBB0_460
; #define LAS __attribute__((address_space(3)))
; #define DOT2(a_, b_, c_) __builtin_amdgcn_fdot2_f32_bf16(__builtin_bit_cast(bf16x2_t, (unsigned)(a_)), __builtin_bit_cast(bf16x2_t, (unsigned)(b_)), (c_), false)
; __global__ void __launch_bounds__(NWAVES * 64, 2) mk_fwd(Args args) {
;     ...
;                     for (int ip = 0; ip < 32; ++ip) {
;                         const u32x2 wv = wvn, av = avn;
;                         { const int ipn = ip < 31 ? ip + 1 : 31; wvn = *(const u32x2*)(w2pl + (size_t)ipn * RW + c0); avn = *(const u32x2*)(w2pl + (size_t)(32 + ipn) * RW + c0); }
; #pragma unroll
;                         for (int tq = 0; tq < 4; ++tq) { const u32x4 x4 = *(LAS const u32x4*)(actP + ip * 16 + tq * 4), y4 = *(LAS const u32x4*)(actP + (32 + ip) * 16 + tq * 4);
; #pragma unroll
;                             for (int e = 0; e < 4; ++e) { lw[tq * 4 + e][0] = DOT2(x4[e], wv.x, lw[tq * 4 + e][0]); lw[tq * 4 + e][1] = DOT2(x4[e], wv.y, lw[tq * 4 + e][1]);
;                                                           la[tq * 4 + e][0] = DOT2(y4[e], av.x, la[tq * 4 + e][0]); la[tq * 4 + e][1] = DOT2(y4[e], av.y, la[tq * 4 + e][1]); } }
	s_waitcnt vmcnt(4)
	v_mov_b64_e32 v[28:29], v[244:245]
	v_mov_b64_e32 v[6:7], v[246:247]
	global_load_dwordx2 v[244:245], v[4:5], off
	global_load_dwordx2 v[246:247], v[248:249], off
	s_add_i32 s93, s92, 0
	v_mov_b32_e32 v30, s93
	ds_read_b128 v[8:11], v30 offset:2048
	ds_read_b128 v[12:15], v30
	ds_read_b128 v[16:19], v30 offset:16
	ds_read_b128 v[20:23], v30 offset:32
	ds_read_b128 v[24:27], v30 offset:48
	s_waitcnt lgkmcnt(4)
	v_dot2c_f32_bf16_e32 v237, v8, v6
	v_dot2c_f32_bf16_e32 v236, v8, v7
	v_dot2c_f32_bf16_e32 v231, v9, v6
	v_dot2c_f32_bf16_e32 v230, v9, v7
	v_dot2c_f32_bf16_e32 v226, v10, v6
	v_dot2c_f32_bf16_e32 v225, v10, v7
	v_dot2c_f32_bf16_e32 v219, v11, v6
	v_dot2c_f32_bf16_e32 v218, v11, v7
	ds_read_b128 v[8:11], v30 offset:2064
	s_add_i32 s92, s92, 64
	s_waitcnt lgkmcnt(4)
	v_dot2c_f32_bf16_e32 v233, v12, v28
	v_dot2c_f32_bf16_e32 v232, v12, v29
	v_dot2c_f32_bf16_e32 v229, v13, v28
	s_waitcnt lgkmcnt(0)
	v_dot2c_f32_bf16_e32 v212, v8, v6
	v_dot2c_f32_bf16_e32 v211, v8, v7
	v_dot2c_f32_bf16_e32 v186, v9, v6
	v_dot2c_f32_bf16_e32 v185, v9, v7
	v_dot2c_f32_bf16_e32 v179, v10, v6
	v_dot2c_f32_bf16_e32 v178, v10, v7
	v_dot2c_f32_bf16_e32 v172, v11, v6
	v_dot2c_f32_bf16_e32 v163, v11, v7
	ds_read_b128 v[8:11], v30 offset:2080
	v_dot2c_f32_bf16_e32 v228, v13, v29
	v_dot2c_f32_bf16_e32 v223, v14, v28
	v_dot2c_f32_bf16_e32 v222, v14, v29
	v_dot2c_f32_bf16_e32 v217, v15, v28
	s_waitcnt lgkmcnt(0)
	v_dot2c_f32_bf16_e32 v157, v8, v6
	v_dot2c_f32_bf16_e32 v154, v8, v7
	v_dot2c_f32_bf16_e32 v150, v9, v6
	v_dot2c_f32_bf16_e32 v149, v9, v7
	v_dot2c_f32_bf16_e32 v122, v10, v6
	v_dot2c_f32_bf16_e32 v141, v10, v7
	v_dot2c_f32_bf16_e32 v135, v11, v6
	v_dot2c_f32_bf16_e32 v134, v11, v7
	ds_read_b128 v[8:11], v30 offset:2096
	v_dot2c_f32_bf16_e32 v215, v15, v29
	v_dot2c_f32_bf16_e32 v209, v16, v28
	v_dot2c_f32_bf16_e32 v208, v16, v29
	v_dot2c_f32_bf16_e32 v184, v17, v28
	v_dot2c_f32_bf16_e32 v183, v17, v29
	v_dot2c_f32_bf16_e32 v177, v18, v28
	v_dot2c_f32_bf16_e32 v176, v18, v29
	v_dot2c_f32_bf16_e32 v160, v19, v28
	v_dot2c_f32_bf16_e32 v159, v19, v29
	v_dot2c_f32_bf16_e32 v153, v20, v28
	v_dot2c_f32_bf16_e32 v152, v20, v29
	v_dot2c_f32_bf16_e32 v146, v21, v28
	v_dot2c_f32_bf16_e32 v145, v21, v29
	v_dot2c_f32_bf16_e32 v140, v22, v28
	v_dot2c_f32_bf16_e32 v139, v22, v29
	v_dot2c_f32_bf16_e32 v133, v23, v28
	v_dot2c_f32_bf16_e32 v132, v23, v29
	v_dot2c_f32_bf16_e32 v124, v24, v28
	v_dot2c_f32_bf16_e32 v123, v24, v29
	s_waitcnt lgkmcnt(0)
	v_dot2c_f32_bf16_e32 v128, v8, v6
	v_dot2c_f32_bf16_e32 v126, v8, v7
	v_dot2c_f32_bf16_e32 v116, v25, v28
	v_dot2c_f32_bf16_e32 v115, v25, v29
	v_dot2c_f32_bf16_e32 v119, v9, v6
	v_dot2c_f32_bf16_e32 v118, v9, v7
	v_dot2c_f32_bf16_e32 v108, v26, v28
	v_dot2c_f32_bf16_e32 v107, v26, v29
	v_dot2c_f32_bf16_e32 v112, v10, v6
	v_dot2c_f32_bf16_e32 v111, v10, v7
	v_dot2c_f32_bf16_e32 v101, v27, v28
	v_dot2c_f32_bf16_e32 v100, v27, v29
	v_dot2c_f32_bf16_e32 v103, v11, v6
	v_dot2c_f32_bf16_e32 v102, v11, v7
	v_lshl_add_u64 v[4:5], v[4:5], 0, s[94:95]
	v_lshl_add_u64 v[248:249], v[248:249], 0, s[94:95]
	s_waitcnt vmcnt(4)
	v_mov_b64_e32 v[28:29], v[74:75]
	v_mov_b64_e32 v[6:7], v[76:77]
	global_load_dwordx2 v[74:75], v[4:5], off
	global_load_dwordx2 v[76:77], v[248:249], off
	s_add_i32 s93, s92, 0
	v_mov_b32_e32 v30, s93
	ds_read_b128 v[8:11], v30 offset:2048
	ds_read_b128 v[12:15], v30
	ds_read_b128 v[16:19], v30 offset:16
	ds_read_b128 v[20:23], v30 offset:32
	ds_read_b128 v[24:27], v30 offset:48
	s_waitcnt lgkmcnt(4)
	v_dot2c_f32_bf16_e32 v237, v8, v6
	v_dot2c_f32_bf16_e32 v236, v8, v7
	v_dot2c_f32_bf16_e32 v231, v9, v6
	v_dot2c_f32_bf16_e32 v230, v9, v7
	v_dot2c_f32_bf16_e32 v226, v10, v6
	v_dot2c_f32_bf16_e32 v225, v10, v7
	v_dot2c_f32_bf16_e32 v219, v11, v6
	v_dot2c_f32_bf16_e32 v218, v11, v7
	ds_read_b128 v[8:11], v30 offset:2064
	s_add_i32 s92, s92, 64
	s_waitcnt lgkmcnt(4)
	v_dot2c_f32_bf16_e32 v233, v12, v28
	v_dot2c_f32_bf16_e32 v232, v12, v29
	v_dot2c_f32_bf16_e32 v229, v13, v28
	s_waitcnt lgkmcnt(0)
	v_dot2c_f32_bf16_e32 v212, v8, v6
	v_dot2c_f32_bf16_e32 v211, v8, v7
	v_dot2c_f32_bf16_e32 v186, v9, v6
	v_dot2c_f32_bf16_e32 v185, v9, v7
	v_dot2c_f32_bf16_e32 v179, v10, v6
	v_dot2c_f32_bf16_e32 v178, v10, v7
	v_dot2c_f32_bf16_e32 v172, v11, v6
	v_dot2c_f32_bf16_e32 v163, v11, v7
	ds_read_b128 v[8:11], v30 offset:2080
	v_dot2c_f32_bf16_e32 v228, v13, v29
	v_dot2c_f32_bf16_e32 v223, v14, v28
	v_dot2c_f32_bf16_e32 v222, v14, v29
	v_dot2c_f32_bf16_e32 v217, v15, v28
	s_waitcnt lgkmcnt(0)
	v_dot2c_f32_bf16_e32 v157, v8, v6
	v_dot2c_f32_bf16_e32 v154, v8, v7
	v_dot2c_f32_bf16_e32 v150, v9, v6
	v_dot2c_f32_bf16_e32 v149, v9, v7
	v_dot2c_f32_bf16_e32 v122, v10, v6
	v_dot2c_f32_bf16_e32 v141, v10, v7
	v_dot2c_f32_bf16_e32 v135, v11, v6
	v_dot2c_f32_bf16_e32 v134, v11, v7
	ds_read_b128 v[8:11], v30 offset:2096
	v_dot2c_f32_bf16_e32 v215, v15, v29
	v_dot2c_f32_bf16_e32 v209, v16, v28
	v_dot2c_f32_bf16_e32 v208, v16, v29
	v_dot2c_f32_bf16_e32 v184, v17, v28
	v_dot2c_f32_bf16_e32 v183, v17, v29
	v_dot2c_f32_bf16_e32 v177, v18, v28
	v_dot2c_f32_bf16_e32 v176, v18, v29
	v_dot2c_f32_bf16_e32 v160, v19, v28
	v_dot2c_f32_bf16_e32 v159, v19, v29
	v_dot2c_f32_bf16_e32 v153, v20, v28
	v_dot2c_f32_bf16_e32 v152, v20, v29
	v_dot2c_f32_bf16_e32 v146, v21, v28
	v_dot2c_f32_bf16_e32 v145, v21, v29
	v_dot2c_f32_bf16_e32 v140, v22, v28
	v_dot2c_f32_bf16_e32 v139, v22, v29
	v_dot2c_f32_bf16_e32 v133, v23, v28
	v_dot2c_f32_bf16_e32 v132, v23, v29
	v_dot2c_f32_bf16_e32 v124, v24, v28
	v_dot2c_f32_bf16_e32 v123, v24, v29
	s_waitcnt lgkmcnt(0)
; #define LAS __attribute__((address_space(3)))
; __device__ __forceinline__ float bflo(unsigned u) { return __uint_as_float(u << 16); }
; __device__ __forceinline__ float bfhi(unsigned u) { return __uint_as_float(u & 0xffff0000u); }
; #define DOT2(a_, b_, c_) __builtin_amdgcn_fdot2_f32_bf16(__builtin_bit_cast(bf16x2_t, (unsigned)(a_)), __builtin_bit_cast(bf16x2_t, (unsigned)(b_)), (c_), false)
; __global__ void __launch_bounds__(NWAVES * 64, 2) mk_fwd(Args args) {
;     ...
;                     for (int ip = 0; ip < 32; ++ip) {
;                         const u32x2 wv = wvn, av = avn;
;                         { const int ipn = ip < 31 ? ip + 1 : 31; wvn = *(const u32x2*)(w2pl + (size_t)ipn * RW + c0); avn = *(const u32x2*)(w2pl + (size_t)(32 + ipn) * RW + c0); }
; #pragma unroll
;                         for (int tq = 0; tq < 4; ++tq) { const u32x4 x4 = *(LAS const u32x4*)(actP + ip * 16 + tq * 4), y4 = *(LAS const u32x4*)(actP + (32 + ip) * 16 + tq * 4);
; #pragma unroll
;                             for (int e = 0; e < 4; ++e) { lw[tq * 4 + e][0] = DOT2(x4[e], wv.x, lw[tq * 4 + e][0]); lw[tq * 4 + e][1] = DOT2(x4[e], wv.y, lw[tq * 4 + e][1]);
;                                                           la[tq * 4 + e][0] = DOT2(y4[e], av.x, la[tq * 4 + e][0]); la[tq * 4 + e][1] = DOT2(y4[e], av.y, la[tq * 4 + e][1]); } }
;                     }
;                     float pr[2], pk[2], pv[2];
;                     if (first) { if (smp) { pr[0] = shst[c0]; pr[1] = shst[c0 + 1]; pk[0] = shst[RW + c0]; pk[1] = shst[RW + c0 + 1]; pv[0] = shst[2 * RW + c0]; pv[1] = shst[2 * RW + c0 + 1]; }
;                                  else { pr[0] = pr[1] = pk[0] = pk[1] = pv[0] = pv[1] = 0.f; } }
;                     else { const unsigned ur = pur[0], uk = puk[0], uv = puv[0];
;                            pr[0] = bflo(ur); pr[1] = bfhi(ur); pk[0] = bflo(uk); pk[1] = bfhi(uk); pv[0] = bflo(uv); pv[1] = bfhi(uv); }
	v_dot2c_f32_bf16_e32 v128, v8, v6
	v_dot2c_f32_bf16_e32 v126, v8, v7
	v_dot2c_f32_bf16_e32 v116, v25, v28
	v_dot2c_f32_bf16_e32 v115, v25, v29
	v_dot2c_f32_bf16_e32 v119, v9, v6
	v_dot2c_f32_bf16_e32 v118, v9, v7
	v_dot2c_f32_bf16_e32 v108, v26, v28
	v_dot2c_f32_bf16_e32 v107, v26, v29
	v_dot2c_f32_bf16_e32 v112, v10, v6
	v_dot2c_f32_bf16_e32 v111, v10, v7
	v_dot2c_f32_bf16_e32 v101, v27, v28
	v_dot2c_f32_bf16_e32 v100, v27, v29
	v_dot2c_f32_bf16_e32 v103, v11, v6
	v_dot2c_f32_bf16_e32 v102, v11, v7
	v_lshl_add_u64 v[4:5], v[4:5], 0, s[94:95]
	v_lshl_add_u64 v[248:249], v[248:249], 0, s[94:95]
	s_waitcnt vmcnt(4)
	v_mov_b64_e32 v[28:29], v[240:241]
	v_mov_b64_e32 v[6:7], v[242:243]
	s_add_i32 s93, s92, 0
	v_mov_b32_e32 v30, s93
	ds_read_b128 v[8:11], v30 offset:2048
	ds_read_b128 v[12:15], v30
	ds_read_b128 v[16:19], v30 offset:16
	ds_read_b128 v[20:23], v30 offset:32
	ds_read_b128 v[24:27], v30 offset:48
	s_waitcnt lgkmcnt(4)
	v_dot2c_f32_bf16_e32 v237, v8, v6
	v_dot2c_f32_bf16_e32 v236, v8, v7
	v_dot2c_f32_bf16_e32 v231, v9, v6
	v_dot2c_f32_bf16_e32 v230, v9, v7
	v_dot2c_f32_bf16_e32 v226, v10, v6
	v_dot2c_f32_bf16_e32 v225, v10, v7
	v_dot2c_f32_bf16_e32 v219, v11, v6
	v_dot2c_f32_bf16_e32 v218, v11, v7
	ds_read_b128 v[8:11], v30 offset:2064
	s_add_i32 s92, s92, 64
	s_waitcnt lgkmcnt(4)
	v_dot2c_f32_bf16_e32 v233, v12, v28
	v_dot2c_f32_bf16_e32 v232, v12, v29
	v_dot2c_f32_bf16_e32 v229, v13, v28
	s_waitcnt lgkmcnt(0)
	v_dot2c_f32_bf16_e32 v212, v8, v6
	v_dot2c_f32_bf16_e32 v211, v8, v7
	v_dot2c_f32_bf16_e32 v186, v9, v6
	v_dot2c_f32_bf16_e32 v185, v9, v7
	v_dot2c_f32_bf16_e32 v179, v10, v6
	v_dot2c_f32_bf16_e32 v178, v10, v7
	v_dot2c_f32_bf16_e32 v172, v11, v6
	v_dot2c_f32_bf16_e32 v163, v11, v7
	ds_read_b128 v[8:11], v30 offset:2080
	v_dot2c_f32_bf16_e32 v228, v13, v29
	v_dot2c_f32_bf16_e32 v223, v14, v28
	v_dot2c_f32_bf16_e32 v222, v14, v29
	v_dot2c_f32_bf16_e32 v217, v15, v28
	s_waitcnt lgkmcnt(0)
	v_dot2c_f32_bf16_e32 v157, v8, v6
	v_dot2c_f32_bf16_e32 v154, v8, v7
	v_dot2c_f32_bf16_e32 v150, v9, v6
	v_dot2c_f32_bf16_e32 v149, v9, v7
	v_dot2c_f32_bf16_e32 v122, v10, v6
	v_dot2c_f32_bf16_e32 v141, v10, v7
	v_dot2c_f32_bf16_e32 v135, v11, v6
	v_dot2c_f32_bf16_e32 v134, v11, v7
	ds_read_b128 v[8:11], v30 offset:2096
	v_dot2c_f32_bf16_e32 v215, v15, v29
	v_dot2c_f32_bf16_e32 v209, v16, v28
	v_dot2c_f32_bf16_e32 v208, v16, v29
	v_dot2c_f32_bf16_e32 v184, v17, v28
	v_dot2c_f32_bf16_e32 v183, v17, v29
	v_dot2c_f32_bf16_e32 v177, v18, v28
	v_dot2c_f32_bf16_e32 v176, v18, v29
	v_dot2c_f32_bf16_e32 v160, v19, v28
	v_dot2c_f32_bf16_e32 v159, v19, v29
	v_dot2c_f32_bf16_e32 v153, v20, v28
	v_dot2c_f32_bf16_e32 v152, v20, v29
	v_dot2c_f32_bf16_e32 v146, v21, v28
	v_dot2c_f32_bf16_e32 v145, v21, v29
	v_dot2c_f32_bf16_e32 v140, v22, v28
	v_dot2c_f32_bf16_e32 v139, v22, v29
	v_dot2c_f32_bf16_e32 v133, v23, v28
	v_dot2c_f32_bf16_e32 v132, v23, v29
	v_dot2c_f32_bf16_e32 v124, v24, v28
	v_dot2c_f32_bf16_e32 v123, v24, v29
	s_waitcnt lgkmcnt(0)
	v_dot2c_f32_bf16_e32 v128, v8, v6
	v_dot2c_f32_bf16_e32 v126, v8, v7
	v_dot2c_f32_bf16_e32 v116, v25, v28
	v_dot2c_f32_bf16_e32 v115, v25, v29
	v_dot2c_f32_bf16_e32 v119, v9, v6
	v_dot2c_f32_bf16_e32 v118, v9, v7
	v_dot2c_f32_bf16_e32 v108, v26, v28
	v_dot2c_f32_bf16_e32 v107, v26, v29
	v_dot2c_f32_bf16_e32 v112, v10, v6
	v_dot2c_f32_bf16_e32 v111, v10, v7
	v_dot2c_f32_bf16_e32 v101, v27, v28
	v_dot2c_f32_bf16_e32 v100, v27, v29
	v_dot2c_f32_bf16_e32 v103, v11, v6
	v_dot2c_f32_bf16_e32 v102, v11, v7
	s_waitcnt vmcnt(2)
	v_mov_b64_e32 v[28:29], v[244:245]
	v_mov_b64_e32 v[6:7], v[246:247]
	s_add_i32 s93, s92, 0
	v_mov_b32_e32 v30, s93
	ds_read_b128 v[8:11], v30 offset:2048
	ds_read_b128 v[12:15], v30
	ds_read_b128 v[16:19], v30 offset:16
	ds_read_b128 v[20:23], v30 offset:32
	ds_read_b128 v[24:27], v30 offset:48
	s_waitcnt lgkmcnt(4)
	v_dot2c_f32_bf16_e32 v237, v8, v6
	v_dot2c_f32_bf16_e32 v236, v8, v7
	v_dot2c_f32_bf16_e32 v231, v9, v6
	v_dot2c_f32_bf16_e32 v230, v9, v7
	v_dot2c_f32_bf16_e32 v226, v10, v6
	v_dot2c_f32_bf16_e32 v225, v10, v7
	v_dot2c_f32_bf16_e32 v219, v11, v6
	v_dot2c_f32_bf16_e32 v218, v11, v7
	ds_read_b128 v[8:11], v30 offset:2064
	s_add_i32 s92, s92, 64
	s_waitcnt lgkmcnt(4)
	v_dot2c_f32_bf16_e32 v233, v12, v28
	v_dot2c_f32_bf16_e32 v232, v12, v29
	v_dot2c_f32_bf16_e32 v229, v13, v28
	s_waitcnt lgkmcnt(0)
	v_dot2c_f32_bf16_e32 v212, v8, v6
	v_dot2c_f32_bf16_e32 v211, v8, v7
	v_dot2c_f32_bf16_e32 v186, v9, v6
	v_dot2c_f32_bf16_e32 v185, v9, v7
	v_dot2c_f32_bf16_e32 v179, v10, v6
	v_dot2c_f32_bf16_e32 v178, v10, v7
	v_dot2c_f32_bf16_e32 v172, v11, v6
	v_dot2c_f32_bf16_e32 v163, v11, v7
	ds_read_b128 v[8:11], v30 offset:2080
	v_dot2c_f32_bf16_e32 v228, v13, v29
	v_dot2c_f32_bf16_e32 v223, v14, v28
	v_dot2c_f32_bf16_e32 v222, v14, v29
	v_dot2c_f32_bf16_e32 v217, v15, v28
	s_waitcnt lgkmcnt(0)
	v_dot2c_f32_bf16_e32 v157, v8, v6
	v_dot2c_f32_bf16_e32 v154, v8, v7
	v_dot2c_f32_bf16_e32 v150, v9, v6
	v_dot2c_f32_bf16_e32 v149, v9, v7
	v_dot2c_f32_bf16_e32 v122, v10, v6
	v_dot2c_f32_bf16_e32 v141, v10, v7
	v_dot2c_f32_bf16_e32 v135, v11, v6
	v_dot2c_f32_bf16_e32 v134, v11, v7
	ds_read_b128 v[8:11], v30 offset:2096
	v_dot2c_f32_bf16_e32 v215, v15, v29
	v_dot2c_f32_bf16_e32 v209, v16, v28
	v_dot2c_f32_bf16_e32 v208, v16, v29
	v_dot2c_f32_bf16_e32 v184, v17, v28
	v_dot2c_f32_bf16_e32 v183, v17, v29
	v_dot2c_f32_bf16_e32 v177, v18, v28
	v_dot2c_f32_bf16_e32 v176, v18, v29
	v_dot2c_f32_bf16_e32 v160, v19, v28
	v_dot2c_f32_bf16_e32 v159, v19, v29
	v_dot2c_f32_bf16_e32 v153, v20, v28
	v_dot2c_f32_bf16_e32 v152, v20, v29
	v_dot2c_f32_bf16_e32 v146, v21, v28
	v_dot2c_f32_bf16_e32 v145, v21, v29
	v_dot2c_f32_bf16_e32 v140, v22, v28
	v_dot2c_f32_bf16_e32 v139, v22, v29
	v_dot2c_f32_bf16_e32 v133, v23, v28
	v_dot2c_f32_bf16_e32 v132, v23, v29
	v_dot2c_f32_bf16_e32 v124, v24, v28
	v_dot2c_f32_bf16_e32 v123, v24, v29
	s_waitcnt lgkmcnt(0)
	v_dot2c_f32_bf16_e32 v128, v8, v6
	v_dot2c_f32_bf16_e32 v126, v8, v7
	v_dot2c_f32_bf16_e32 v116, v25, v28
	v_dot2c_f32_bf16_e32 v115, v25, v29
	v_dot2c_f32_bf16_e32 v119, v9, v6
	v_dot2c_f32_bf16_e32 v118, v9, v7
	v_dot2c_f32_bf16_e32 v108, v26, v28
	v_dot2c_f32_bf16_e32 v107, v26, v29
	v_dot2c_f32_bf16_e32 v112, v10, v6
	v_dot2c_f32_bf16_e32 v111, v10, v7
	v_dot2c_f32_bf16_e32 v101, v27, v28
	v_dot2c_f32_bf16_e32 v100, v27, v29
	v_dot2c_f32_bf16_e32 v103, v11, v6
	v_dot2c_f32_bf16_e32 v102, v11, v7
	s_waitcnt vmcnt(0)
	ds_read_b128 v[28:31], v3 offset:1984
	ds_read_b128 v[20:23], v3 offset:2000
	ds_read_b128 v[12:15], v3 offset:2016
	ds_read_b128 v[4:7], v3 offset:2032
	ds_read_b128 v[32:35], v3 offset:4032
	ds_read_b128 v[24:27], v3 offset:4048
	ds_read_b128 v[16:19], v3 offset:4064
	ds_read_b128 v[8:11], v3 offset:4080
	s_mov_b64 s[92:93], -1
	s_and_b64 vcc, exec, s[88:89]
	s_cbranch_vccz .LBB0_463
	v_lshlrev_b32_e32 v86, 16, v81
	v_and_b32_e32 v87, 0xffff0000, v81
	v_lshlrev_b32_e32 v84, 16, v80
	v_and_b32_e32 v85, 0xffff0000, v80
	v_lshlrev_b32_e32 v82, 16, v227
	v_and_b32_e32 v83, 0xffff0000, v227
	s_mov_b64 s[92:93], 0
